# pool_up GEMM epilogue: gate loads of row pairs 2-4 (12 per wave) issued at the top behind the first pair's loads; per-pair vmcnt(0)/(2) ladders replaced by counted waits
# baseline (speedup 1.0000x reference)
; __device__ __forceinline__ float sigmoidf_(float g) { return __builtin_amdgcn_rcpf(1.f + __expf(-g)); }
; __device__ __forceinline__ u32x4 pack8(const f32x4& a, const f32x4& b) { u32x4 w; w.x = cvt_pk_bf16(a[0], a[1]); w.y = cvt_pk_bf16(a[2], a[3]); w.z = cvt_pk_bf16(b[0], b[1]); w.w = cvt_pk_bf16(b[2], b[3]); return w; }
; __device__ __forceinline__ void unpack8(const u32x4& w, float (&v)[8]) { v[0] = bf_lo(w.x); v[1] = bf_hi(w.x); v[2] = bf_lo(w.y); v[3] = bf_hi(w.y); v[4] = bf_lo(w.z); v[5] = bf_hi(w.z); v[6] = bf_lo(w.w); v[7] = bf_hi(w.w); }
;     __device__ __forceinline__ void apply(const Ld& d, int row, int c0, int, int, int, const f32x4& a0, const f32x4& b0, const f32x4& a1, const f32x4& b1) const { half(d.g0, d.p0, row, c0, a0, b0); half(d.g1, d.p1, row, c0 + 128, a1, b1); }
;     __device__ __forceinline__ void half(const u32x4& gw, int row, int col, const f32x4& a, const f32x4& b) const {
;         float g[8]; unpack8(gw, g);
;         f32x4 r0, r1;
; #pragma unroll
;         for (int i = 0; i < 4; ++i) { r0[i] = a[i] * sigmoidf_(g[i]); r1[i] = b[i] * sigmoidf_(g[4 + i]); }
;         *(u32x4*)(proj + (size_t)row * PW + C_MPOOL + col) = pack8(r0, r1);
;     }
;     __device__ __forceinline__ void apply(const Ld& d, int row, int c0, int, int, int, const f32x4& a0, const f32x4& b0, const f32x4& a1, const f32x4& b1) const { half(d.g0, row, c0, a0, b0); half(d.g1, row, c0 + 128, a1, b1); }
.LBB0_286:
	s_andn2_b64 vcc, exec, s[0:1]
	s_cbranch_vccnz .LBB0_288
	v_lshl_or_b32 v134, s71, 8, v241
	v_ashrrev_i32_e32 v135, 31, v134
	v_lshl_add_u32 v0, s63, 8, v17
	v_mov_b64_e32 v[146:147], s[74:75]
	v_mad_i64_i32 v[136:137], s[0:1], v0, s29, v[146:147]
	v_lshlrev_b64 v[148:149], 1, v[134:135]
	v_lshl_add_u64 v[152:153], v[136:137], 0, v[148:149]
	v_add_co_u32_e32 v134, vcc, 0x1000, v152
	s_nop 1
	v_addc_co_u32_e32 v135, vcc, 0, v153, vcc
	global_load_dwordx4 v[154:157], v[134:135], off offset:1024
	global_load_dwordx4 v[142:145], v[134:135], off offset:1280
	v_or_b32_e32 v134, 16, v0
	v_mad_i64_i32 v[134:135], s[0:1], v134, s29, v[146:147]
	v_lshl_add_u64 v[150:151], v[134:135], 0, v[148:149]
	v_add_co_u32_e32 v134, vcc, 0x1000, v150
	s_waitcnt vmcnt(0)
	v_lshlrev_b32_e32 v158, 16, v154
	v_addc_co_u32_e32 v135, vcc, 0, v151, vcc
	global_load_dwordx4 v[138:141], v[134:135], off offset:1024
	s_nop 0
	global_load_dwordx4 v[134:137], v[134:135], off offset:1280
	s_movk_i32 s48, 0x1000
	s_mov_b32 s49, 0
	v_add_u32_e32 v250, 32, v0
	v_mad_i64_i32 v[248:249], s[50:51], v250, s29, v[146:147]
	v_lshl_add_u64 v[248:249], v[248:249], 0, v[148:149]
	v_lshl_add_u64 v[248:249], v[248:249], 0, s[48:49]
	global_load_dwordx4 v[162:165], v[248:249], off offset:1024
	global_load_dwordx4 v[166:169], v[248:249], off offset:1280
	v_add_u32_e32 v250, 48, v0
	v_mad_i64_i32 v[248:249], s[50:51], v250, s29, v[146:147]
	v_lshl_add_u64 v[248:249], v[248:249], 0, v[148:149]
	v_lshl_add_u64 v[248:249], v[248:249], 0, s[48:49]
	global_load_dwordx4 v[170:173], v[248:249], off offset:1024
	global_load_dwordx4 v[174:177], v[248:249], off offset:1280
	v_add_u32_e32 v250, 0x80, v0
	v_mad_i64_i32 v[248:249], s[50:51], v250, s29, v[146:147]
	v_lshl_add_u64 v[248:249], v[248:249], 0, v[148:149]
	v_lshl_add_u64 v[248:249], v[248:249], 0, s[48:49]
	global_load_dwordx4 v[178:181], v[248:249], off offset:1024
	global_load_dwordx4 v[204:207], v[248:249], off offset:1280
	v_add_u32_e32 v250, 0x90, v0
	v_mad_i64_i32 v[248:249], s[50:51], v250, s29, v[146:147]
	v_lshl_add_u64 v[248:249], v[248:249], 0, v[148:149]
	v_lshl_add_u64 v[248:249], v[248:249], 0, s[48:49]
	global_load_dwordx4 v[208:211], v[248:249], off offset:1024
	global_load_dwordx4 v[212:215], v[248:249], off offset:1280
	v_add_u32_e32 v250, 0xa0, v0
	v_mad_i64_i32 v[248:249], s[50:51], v250, s29, v[146:147]
	v_lshl_add_u64 v[248:249], v[248:249], 0, v[148:149]
	v_lshl_add_u64 v[248:249], v[248:249], 0, s[48:49]
	global_load_dwordx4 v[216:219], v[248:249], off offset:1024
	global_load_dwordx4 v[220:223], v[248:249], off offset:1280
	v_add_u32_e32 v250, 0xb0, v0
	v_mad_i64_i32 v[248:249], s[50:51], v250, s29, v[146:147]
	v_lshl_add_u64 v[248:249], v[248:249], 0, v[148:149]
	v_lshl_add_u64 v[248:249], v[248:249], 0, s[48:49]
	global_load_dwordx4 v[224:227], v[248:249], off offset:1024
	global_load_dwordx4 v[244:247], v[248:249], off offset:1280
	v_and_b32_e32 v154, 0xffff0000, v154
	v_lshlrev_b32_e32 v159, 16, v155
	v_and_b32_e32 v155, 0xffff0000, v155
	v_lshlrev_b32_e32 v160, 16, v156
	v_and_b32_e32 v156, 0xffff0000, v156
	v_lshlrev_b32_e32 v161, 16, v157
	v_and_b32_e32 v157, 0xffff0000, v157
	v_mul_f32_e32 v154, 0xbfb8aa3b, v154
	v_mul_f32_e32 v158, 0xbfb8aa3b, v158
	v_exp_f32_e32 v154, v154
	v_mul_f32_e32 v156, 0xbfb8aa3b, v156
	v_mul_f32_e32 v155, 0xbfb8aa3b, v155
	v_mul_f32_e32 v157, 0xbfb8aa3b, v157
	v_exp_f32_e32 v158, v158
	v_mul_f32_e32 v160, 0xbfb8aa3b, v160
	v_exp_f32_e32 v156, v156
	v_mul_f32_e32 v159, 0xbfb8aa3b, v159
	v_mul_f32_e32 v161, 0xbfb8aa3b, v161
	v_exp_f32_e32 v155, v155
	v_exp_f32_e32 v157, v157
	v_exp_f32_e32 v160, v160
	v_exp_f32_e32 v159, v159
	v_exp_f32_e32 v161, v161
	v_add_f32_e32 v154, 1.0, v154
	v_add_f32_e32 v158, 1.0, v158
	v_rcp_f32_e32 v154, v154
	v_add_f32_e32 v156, 1.0, v156
	v_add_f32_e32 v155, 1.0, v155
	v_add_f32_e32 v157, 1.0, v157
	v_rcp_f32_e32 v158, v158
	v_add_f32_e32 v160, 1.0, v160
	v_rcp_f32_e32 v156, v156
	v_add_f32_e32 v159, 1.0, v159
	v_add_f32_e32 v161, 1.0, v161
	v_rcp_f32_e32 v155, v155
	v_rcp_f32_e32 v157, v157
	v_rcp_f32_e32 v160, v160
	v_rcp_f32_e32 v159, v159
	v_rcp_f32_e32 v161, v161
	v_mul_f32_e32 v154, v131, v154
	v_mul_f32_e32 v158, v130, v158
	v_mul_f32_e32 v156, v127, v156
	v_mul_f32_e32 v155, v133, v155
	v_mul_f32_e32 v157, v129, v157
	v_cvt_pk_bf16_f32 v154, v158, v154
	v_mul_f32_e32 v160, v126, v160
	v_mul_f32_e32 v159, v132, v159
	v_mul_f32_e32 v161, v128, v161
	v_cvt_pk_bf16_f32 v155, v159, v155
	v_cvt_pk_bf16_f32 v156, v160, v156
	v_cvt_pk_bf16_f32 v157, v161, v157
	global_store_dwordx4 v[152:153], v[154:157], off offset:2048
	s_nop 1
	v_lshlrev_b32_e32 v154, 16, v142
	v_and_b32_e32 v142, 0xffff0000, v142
	v_lshlrev_b32_e32 v155, 16, v143
	v_and_b32_e32 v143, 0xffff0000, v143
	v_lshlrev_b32_e32 v156, 16, v144
	v_and_b32_e32 v144, 0xffff0000, v144
	v_lshlrev_b32_e32 v157, 16, v145
	v_and_b32_e32 v145, 0xffff0000, v145
	v_mul_f32_e32 v142, 0xbfb8aa3b, v142
	v_mul_f32_e32 v154, 0xbfb8aa3b, v154
	v_exp_f32_e32 v142, v142
	v_mul_f32_e32 v144, 0xbfb8aa3b, v144
	v_mul_f32_e32 v143, 0xbfb8aa3b, v143
	v_mul_f32_e32 v145, 0xbfb8aa3b, v145
	v_exp_f32_e32 v154, v154
	v_mul_f32_e32 v156, 0xbfb8aa3b, v156
	v_exp_f32_e32 v144, v144
	v_mul_f32_e32 v155, 0xbfb8aa3b, v155
	v_mul_f32_e32 v157, 0xbfb8aa3b, v157
	v_exp_f32_e32 v143, v143
	v_exp_f32_e32 v145, v145
	v_exp_f32_e32 v156, v156
	v_exp_f32_e32 v155, v155
	v_exp_f32_e32 v157, v157
	v_add_f32_e32 v142, 1.0, v142
	v_add_f32_e32 v154, 1.0, v154
	v_rcp_f32_e32 v142, v142
	v_add_f32_e32 v144, 1.0, v144
	v_add_f32_e32 v143, 1.0, v143
	v_add_f32_e32 v145, 1.0, v145
	v_rcp_f32_e32 v154, v154
	v_add_f32_e32 v156, 1.0, v156
	v_rcp_f32_e32 v144, v144
	v_add_f32_e32 v155, 1.0, v155
	v_add_f32_e32 v157, 1.0, v157
	v_rcp_f32_e32 v143, v143
	v_rcp_f32_e32 v145, v145
	v_rcp_f32_e32 v156, v156
	v_rcp_f32_e32 v155, v155
	v_rcp_f32_e32 v157, v157
	v_mul_f32_e32 v142, v123, v142
	v_mul_f32_e32 v154, v122, v154
	v_mul_f32_e32 v144, v119, v144
	v_mul_f32_e32 v143, v125, v143
	v_mul_f32_e32 v145, v121, v145
	v_cvt_pk_bf16_f32 v142, v154, v142
	v_mul_f32_e32 v156, v118, v156
	v_mul_f32_e32 v155, v124, v155
	v_mul_f32_e32 v157, v120, v157
	v_cvt_pk_bf16_f32 v143, v155, v143
	v_cvt_pk_bf16_f32 v144, v156, v144
	v_cvt_pk_bf16_f32 v145, v157, v145
	global_store_dwordx4 v[152:153], v[142:145], off offset:2304
	s_waitcnt vmcnt(14)
; __device__ __forceinline__ float sigmoidf_(float g) { return __builtin_amdgcn_rcpf(1.f + __expf(-g)); }
; __device__ __forceinline__ u32x4 pack8(const f32x4& a, const f32x4& b) { u32x4 w; w.x = cvt_pk_bf16(a[0], a[1]); w.y = cvt_pk_bf16(a[2], a[3]); w.z = cvt_pk_bf16(b[0], b[1]); w.w = cvt_pk_bf16(b[2], b[3]); return w; }
; __device__ __forceinline__ void unpack8(const u32x4& w, float (&v)[8]) { v[0] = bf_lo(w.x); v[1] = bf_hi(w.x); v[2] = bf_lo(w.y); v[3] = bf_hi(w.y); v[4] = bf_lo(w.z); v[5] = bf_hi(w.z); v[6] = bf_lo(w.w); v[7] = bf_hi(w.w); }
;     __device__ __forceinline__ void apply(const Ld& d, int row, int c0, int, int, int, const f32x4& a0, const f32x4& b0, const f32x4& a1, const f32x4& b1) const { half(d.g0, d.p0, row, c0, a0, b0); half(d.g1, d.p1, row, c0 + 128, a1, b1); }
;     __device__ __forceinline__ void half(const u32x4& gw, int row, int col, const f32x4& a, const f32x4& b) const {
;         float g[8]; unpack8(gw, g);
;         f32x4 r0, r1;
; #pragma unroll
;         for (int i = 0; i < 4; ++i) { r0[i] = a[i] * sigmoidf_(g[i]); r1[i] = b[i] * sigmoidf_(g[4 + i]); }
;         *(u32x4*)(proj + (size_t)row * PW + C_MPOOL + col) = pack8(r0, r1);
;     }
;     __device__ __forceinline__ void apply(const Ld& d, int row, int c0, int, int, int, const f32x4& a0, const f32x4& b0, const f32x4& a1, const f32x4& b1) const { half(d.g0, row, c0, a0, b0); half(d.g1, row, c0 + 128, a1, b1); }
	s_nop 0
	v_lshlrev_b32_e32 v142, 16, v138
	v_and_b32_e32 v138, 0xffff0000, v138
	v_lshlrev_b32_e32 v143, 16, v139
	v_and_b32_e32 v139, 0xffff0000, v139
	v_lshlrev_b32_e32 v144, 16, v140
	v_and_b32_e32 v140, 0xffff0000, v140
	v_lshlrev_b32_e32 v145, 16, v141
	v_and_b32_e32 v141, 0xffff0000, v141
	v_mul_f32_e32 v138, 0xbfb8aa3b, v138
	v_mul_f32_e32 v142, 0xbfb8aa3b, v142
	v_exp_f32_e32 v138, v138
	v_mul_f32_e32 v140, 0xbfb8aa3b, v140
	v_mul_f32_e32 v139, 0xbfb8aa3b, v139
	v_mul_f32_e32 v141, 0xbfb8aa3b, v141
	v_exp_f32_e32 v142, v142
	v_mul_f32_e32 v144, 0xbfb8aa3b, v144
	v_exp_f32_e32 v140, v140
	v_mul_f32_e32 v143, 0xbfb8aa3b, v143
	v_mul_f32_e32 v145, 0xbfb8aa3b, v145
	v_exp_f32_e32 v139, v139
	v_exp_f32_e32 v141, v141
	v_exp_f32_e32 v144, v144
	v_exp_f32_e32 v143, v143
	v_exp_f32_e32 v145, v145
	v_add_f32_e32 v138, 1.0, v138
	v_add_f32_e32 v142, 1.0, v142
	v_rcp_f32_e32 v138, v138
	v_add_f32_e32 v140, 1.0, v140
	v_add_f32_e32 v139, 1.0, v139
	v_add_f32_e32 v141, 1.0, v141
	v_rcp_f32_e32 v142, v142
	v_add_f32_e32 v144, 1.0, v144
	v_rcp_f32_e32 v140, v140
	v_add_f32_e32 v143, 1.0, v143
	v_add_f32_e32 v145, 1.0, v145
	v_rcp_f32_e32 v139, v139
	v_rcp_f32_e32 v141, v141
	v_rcp_f32_e32 v144, v144
	v_rcp_f32_e32 v143, v143
	v_rcp_f32_e32 v145, v145
	v_mul_f32_e32 v138, v115, v138
	v_mul_f32_e32 v142, v114, v142
	v_mul_f32_e32 v140, v111, v140
	v_mul_f32_e32 v139, v117, v139
	v_mul_f32_e32 v141, v113, v141
	v_cvt_pk_bf16_f32 v138, v142, v138
	v_mul_f32_e32 v144, v110, v144
	v_mul_f32_e32 v143, v116, v143
	v_mul_f32_e32 v145, v112, v145
	v_cvt_pk_bf16_f32 v139, v143, v139
	v_cvt_pk_bf16_f32 v140, v144, v140
	v_cvt_pk_bf16_f32 v141, v145, v141
	global_store_dwordx4 v[150:151], v[138:141], off offset:2048
	s_nop 1
	v_lshlrev_b32_e32 v138, 16, v134
	v_and_b32_e32 v134, 0xffff0000, v134
	v_lshlrev_b32_e32 v139, 16, v135
	v_and_b32_e32 v135, 0xffff0000, v135
	v_lshlrev_b32_e32 v140, 16, v136
	v_and_b32_e32 v136, 0xffff0000, v136
	v_lshlrev_b32_e32 v141, 16, v137
	v_and_b32_e32 v137, 0xffff0000, v137
	v_mul_f32_e32 v134, 0xbfb8aa3b, v134
	v_mul_f32_e32 v138, 0xbfb8aa3b, v138
	v_exp_f32_e32 v134, v134
	v_mul_f32_e32 v136, 0xbfb8aa3b, v136
	v_mul_f32_e32 v135, 0xbfb8aa3b, v135
	v_mul_f32_e32 v137, 0xbfb8aa3b, v137
	v_exp_f32_e32 v138, v138
	v_mul_f32_e32 v140, 0xbfb8aa3b, v140
	v_exp_f32_e32 v136, v136
	v_mul_f32_e32 v139, 0xbfb8aa3b, v139
	v_mul_f32_e32 v141, 0xbfb8aa3b, v141
	v_exp_f32_e32 v135, v135
	v_exp_f32_e32 v137, v137
	v_exp_f32_e32 v140, v140
	v_exp_f32_e32 v139, v139
	v_exp_f32_e32 v141, v141
	v_add_f32_e32 v134, 1.0, v134
	v_add_f32_e32 v138, 1.0, v138
	v_rcp_f32_e32 v134, v134
	v_add_f32_e32 v136, 1.0, v136
	v_add_f32_e32 v135, 1.0, v135
	v_add_f32_e32 v137, 1.0, v137
	v_rcp_f32_e32 v138, v138
	v_add_f32_e32 v140, 1.0, v140
	v_rcp_f32_e32 v136, v136
	v_add_f32_e32 v139, 1.0, v139
	v_add_f32_e32 v141, 1.0, v141
	v_rcp_f32_e32 v135, v135
	v_rcp_f32_e32 v137, v137
	v_rcp_f32_e32 v140, v140
	v_rcp_f32_e32 v139, v139
	v_rcp_f32_e32 v141, v141
	v_mul_f32_e32 v134, v107, v134
	v_mul_f32_e32 v138, v106, v138
	v_mul_f32_e32 v136, v103, v136
	v_mul_f32_e32 v135, v109, v135
	v_mul_f32_e32 v137, v105, v137
	v_cvt_pk_bf16_f32 v134, v138, v134
	v_mul_f32_e32 v140, v102, v140
	v_mul_f32_e32 v139, v108, v139
	v_mul_f32_e32 v141, v104, v141
	v_cvt_pk_bf16_f32 v135, v139, v135
	v_cvt_pk_bf16_f32 v136, v140, v136
	v_cvt_pk_bf16_f32 v137, v141, v137
	global_store_dwordx4 v[150:151], v[134:137], off offset:2304
	s_nop 1
	v_or_b32_e32 v134, 32, v0
	v_mad_i64_i32 v[134:135], s[0:1], v134, s29, v[146:147]
	v_lshl_add_u64 v[144:145], v[134:135], 0, v[148:149]
	v_add_co_u32_e32 v134, vcc, s98, v144
	s_nop 1
	v_addc_co_u32_e32 v135, vcc, 0, v145, vcc
	s_waitcnt vmcnt(12)
	v_mov_b32_e32 v150, v162
	v_mov_b32_e32 v151, v163
	v_mov_b32_e32 v152, v164
	v_mov_b32_e32 v153, v165
	v_mov_b32_e32 v154, v166
	v_mov_b32_e32 v155, v167
	v_mov_b32_e32 v156, v168
	v_mov_b32_e32 v157, v169
	v_or_b32_e32 v134, 48, v0
	v_mad_i64_i32 v[134:135], s[0:1], v134, s29, v[146:147]
	v_lshl_add_u64 v[142:143], v[134:135], 0, v[148:149]
	v_add_co_u32_e32 v134, vcc, s98, v142
	s_nop 0
	v_lshlrev_b32_e32 v158, 16, v150
	v_addc_co_u32_e32 v135, vcc, 0, v143, vcc
	v_mov_b32_e32 v138, v170
	v_mov_b32_e32 v139, v171
	v_mov_b32_e32 v140, v172
	v_mov_b32_e32 v141, v173
	s_nop 0
	v_mov_b32_e32 v134, v174
	v_mov_b32_e32 v135, v175
	v_mov_b32_e32 v136, v176
	v_mov_b32_e32 v137, v177
	v_and_b32_e32 v150, 0xffff0000, v150
	v_lshlrev_b32_e32 v159, 16, v151
	v_and_b32_e32 v151, 0xffff0000, v151
	v_lshlrev_b32_e32 v160, 16, v152
	v_and_b32_e32 v152, 0xffff0000, v152
	v_lshlrev_b32_e32 v161, 16, v153
	v_and_b32_e32 v153, 0xffff0000, v153
	v_mul_f32_e32 v150, 0xbfb8aa3b, v150
	v_mul_f32_e32 v152, 0xbfb8aa3b, v152
	v_mul_f32_e32 v151, 0xbfb8aa3b, v151
	v_mul_f32_e32 v153, 0xbfb8aa3b, v153
	v_mul_f32_e32 v158, 0xbfb8aa3b, v158
	v_mul_f32_e32 v160, 0xbfb8aa3b, v160
	v_exp_f32_e32 v150, v150
	v_exp_f32_e32 v152, v152
	v_mul_f32_e32 v159, 0xbfb8aa3b, v159
	v_mul_f32_e32 v161, 0xbfb8aa3b, v161
	v_exp_f32_e32 v151, v151
	v_exp_f32_e32 v153, v153
	v_exp_f32_e32 v158, v158
	v_exp_f32_e32 v160, v160
	v_exp_f32_e32 v159, v159
	v_exp_f32_e32 v161, v161
	v_add_f32_e32 v150, 1.0, v150
	v_add_f32_e32 v152, 1.0, v152
	v_add_f32_e32 v151, 1.0, v151
	v_add_f32_e32 v153, 1.0, v153
	v_add_f32_e32 v158, 1.0, v158
	v_add_f32_e32 v160, 1.0, v160
	v_rcp_f32_e32 v150, v150
	v_rcp_f32_e32 v152, v152
	v_add_f32_e32 v159, 1.0, v159
	v_add_f32_e32 v161, 1.0, v161
	v_rcp_f32_e32 v151, v151
	v_rcp_f32_e32 v153, v153
	v_rcp_f32_e32 v158, v158
	v_rcp_f32_e32 v160, v160
	v_rcp_f32_e32 v159, v159
	v_rcp_f32_e32 v161, v161
	v_mul_f32_e32 v150, v99, v150
; __device__ __forceinline__ float sigmoidf_(float g) { return __builtin_amdgcn_rcpf(1.f + __expf(-g)); }
; __device__ __forceinline__ u32x4 pack8(const f32x4& a, const f32x4& b) { u32x4 w; w.x = cvt_pk_bf16(a[0], a[1]); w.y = cvt_pk_bf16(a[2], a[3]); w.z = cvt_pk_bf16(b[0], b[1]); w.w = cvt_pk_bf16(b[2], b[3]); return w; }
; __device__ __forceinline__ void unpack8(const u32x4& w, float (&v)[8]) { v[0] = bf_lo(w.x); v[1] = bf_hi(w.x); v[2] = bf_lo(w.y); v[3] = bf_hi(w.y); v[4] = bf_lo(w.z); v[5] = bf_hi(w.z); v[6] = bf_lo(w.w); v[7] = bf_hi(w.w); }
;     __device__ __forceinline__ void apply(const Ld& d, int row, int c0, int, int, int, const f32x4& a0, const f32x4& b0, const f32x4& a1, const f32x4& b1) const { half(d.g0, d.p0, row, c0, a0, b0); half(d.g1, d.p1, row, c0 + 128, a1, b1); }
;     __device__ __forceinline__ void half(const u32x4& gw, int row, int col, const f32x4& a, const f32x4& b) const {
;         float g[8]; unpack8(gw, g);
;         f32x4 r0, r1;
; #pragma unroll
;         for (int i = 0; i < 4; ++i) { r0[i] = a[i] * sigmoidf_(g[i]); r1[i] = b[i] * sigmoidf_(g[4 + i]); }
;         *(u32x4*)(proj + (size_t)row * PW + C_MPOOL + col) = pack8(r0, r1);
;     }
;     __device__ __forceinline__ void apply(const Ld& d, int row, int c0, int, int, int, const f32x4& a0, const f32x4& b0, const f32x4& a1, const f32x4& b1) const { half(d.g0, row, c0, a0, b0); half(d.g1, row, c0 + 128, a1, b1); }
	v_mul_f32_e32 v152, v95, v152
	v_mul_f32_e32 v151, v101, v151
	v_mul_f32_e32 v153, v97, v153
	v_mul_f32_e32 v158, v98, v158
	v_mul_f32_e32 v160, v94, v160
	v_mul_f32_e32 v159, v100, v159
	v_mul_f32_e32 v161, v96, v161
	v_cvt_pk_bf16_f32 v150, v158, v150
	v_cvt_pk_bf16_f32 v151, v159, v151
	v_cvt_pk_bf16_f32 v152, v160, v152
	v_cvt_pk_bf16_f32 v153, v161, v153
	global_store_dwordx4 v[144:145], v[150:153], off offset:2048
	s_nop 1
	v_lshlrev_b32_e32 v150, 16, v154
	v_and_b32_e32 v151, 0xffff0000, v154
	v_lshlrev_b32_e32 v152, 16, v155
	v_and_b32_e32 v153, 0xffff0000, v155
	v_lshlrev_b32_e32 v154, 16, v156
	v_and_b32_e32 v155, 0xffff0000, v156
	v_lshlrev_b32_e32 v156, 16, v157
	v_and_b32_e32 v157, 0xffff0000, v157
	v_mul_f32_e32 v150, 0xbfb8aa3b, v150
	v_mul_f32_e32 v151, 0xbfb8aa3b, v151
	v_mul_f32_e32 v152, 0xbfb8aa3b, v152
	v_mul_f32_e32 v153, 0xbfb8aa3b, v153
	v_exp_f32_e32 v150, v150
	v_mul_f32_e32 v154, 0xbfb8aa3b, v154
	v_exp_f32_e32 v151, v151
	v_mul_f32_e32 v155, 0xbfb8aa3b, v155
	v_exp_f32_e32 v152, v152
	v_mul_f32_e32 v156, 0xbfb8aa3b, v156
	v_exp_f32_e32 v153, v153
	v_mul_f32_e32 v157, 0xbfb8aa3b, v157
	v_exp_f32_e32 v154, v154
	v_exp_f32_e32 v155, v155
	v_exp_f32_e32 v156, v156
	v_exp_f32_e32 v157, v157
	v_add_f32_e32 v150, 1.0, v150
	v_add_f32_e32 v151, 1.0, v151
	v_add_f32_e32 v152, 1.0, v152
	v_add_f32_e32 v153, 1.0, v153
	v_rcp_f32_e32 v150, v150
	v_add_f32_e32 v154, 1.0, v154
	v_rcp_f32_e32 v151, v151
	v_add_f32_e32 v155, 1.0, v155
	v_rcp_f32_e32 v152, v152
	v_add_f32_e32 v156, 1.0, v156
	v_rcp_f32_e32 v153, v153
	v_add_f32_e32 v157, 1.0, v157
	v_rcp_f32_e32 v154, v154
	v_rcp_f32_e32 v155, v155
	v_rcp_f32_e32 v156, v156
	v_rcp_f32_e32 v157, v157
	v_mul_f32_e32 v150, v90, v150
	v_mul_f32_e32 v151, v91, v151
	v_mul_f32_e32 v152, v92, v152
	v_mul_f32_e32 v153, v93, v153
	v_mul_f32_e32 v154, v86, v154
	v_mul_f32_e32 v155, v87, v155
	v_mul_f32_e32 v156, v88, v156
	v_mul_f32_e32 v157, v89, v157
	v_cvt_pk_bf16_f32 v150, v150, v151
	v_cvt_pk_bf16_f32 v151, v152, v153
	v_cvt_pk_bf16_f32 v152, v154, v155
	v_cvt_pk_bf16_f32 v153, v156, v157
	global_store_dwordx4 v[144:145], v[150:153], off offset:2304
	s_nop 0
	v_lshlrev_b32_e32 v144, 16, v138
	v_and_b32_e32 v138, 0xffff0000, v138
	v_lshlrev_b32_e32 v145, 16, v139
	v_and_b32_e32 v139, 0xffff0000, v139
	v_lshlrev_b32_e32 v150, 16, v140
	v_and_b32_e32 v140, 0xffff0000, v140
	v_lshlrev_b32_e32 v151, 16, v141
	v_and_b32_e32 v141, 0xffff0000, v141
	v_mul_f32_e32 v138, 0xbfb8aa3b, v138
	v_mul_f32_e32 v144, 0xbfb8aa3b, v144
	v_exp_f32_e32 v138, v138
	v_mul_f32_e32 v140, 0xbfb8aa3b, v140
	v_mul_f32_e32 v139, 0xbfb8aa3b, v139
	v_mul_f32_e32 v141, 0xbfb8aa3b, v141
	v_exp_f32_e32 v144, v144
	v_mul_f32_e32 v150, 0xbfb8aa3b, v150
	v_exp_f32_e32 v140, v140
	v_mul_f32_e32 v145, 0xbfb8aa3b, v145
	v_mul_f32_e32 v151, 0xbfb8aa3b, v151
	v_exp_f32_e32 v139, v139
	v_exp_f32_e32 v141, v141
	v_exp_f32_e32 v150, v150
	v_exp_f32_e32 v145, v145
	v_exp_f32_e32 v151, v151
	v_add_f32_e32 v138, 1.0, v138
	v_add_f32_e32 v144, 1.0, v144
	v_rcp_f32_e32 v138, v138
	v_add_f32_e32 v140, 1.0, v140
	v_add_f32_e32 v139, 1.0, v139
	v_add_f32_e32 v141, 1.0, v141
	v_rcp_f32_e32 v144, v144
	v_add_f32_e32 v150, 1.0, v150
	v_rcp_f32_e32 v140, v140
	v_add_f32_e32 v145, 1.0, v145
	v_add_f32_e32 v151, 1.0, v151
	v_rcp_f32_e32 v139, v139
	v_rcp_f32_e32 v141, v141
	v_rcp_f32_e32 v150, v150
	v_rcp_f32_e32 v145, v145
	v_rcp_f32_e32 v151, v151
	v_mul_f32_e32 v138, v83, v138
	v_mul_f32_e32 v144, v82, v144
	v_mul_f32_e32 v140, v79, v140
	v_mul_f32_e32 v139, v85, v139
	v_mul_f32_e32 v141, v81, v141
	v_cvt_pk_bf16_f32 v138, v144, v138
	v_mul_f32_e32 v150, v78, v150
	v_mul_f32_e32 v145, v84, v145
	v_mul_f32_e32 v151, v80, v151
	v_cvt_pk_bf16_f32 v139, v145, v139
	v_cvt_pk_bf16_f32 v140, v150, v140
	v_cvt_pk_bf16_f32 v141, v151, v141
	global_store_dwordx4 v[142:143], v[138:141], off offset:2048
	s_nop 1
	v_lshlrev_b32_e32 v138, 16, v134
	v_and_b32_e32 v134, 0xffff0000, v134
	v_lshlrev_b32_e32 v139, 16, v135
	v_and_b32_e32 v135, 0xffff0000, v135
	v_lshlrev_b32_e32 v140, 16, v136
	v_and_b32_e32 v136, 0xffff0000, v136
	v_lshlrev_b32_e32 v141, 16, v137
	v_and_b32_e32 v137, 0xffff0000, v137
	v_mul_f32_e32 v134, 0xbfb8aa3b, v134
	v_mul_f32_e32 v138, 0xbfb8aa3b, v138
	v_exp_f32_e32 v134, v134
	v_mul_f32_e32 v136, 0xbfb8aa3b, v136
	v_mul_f32_e32 v135, 0xbfb8aa3b, v135
	v_mul_f32_e32 v137, 0xbfb8aa3b, v137
	v_exp_f32_e32 v138, v138
	v_mul_f32_e32 v140, 0xbfb8aa3b, v140
	v_exp_f32_e32 v136, v136
	v_mul_f32_e32 v139, 0xbfb8aa3b, v139
	v_mul_f32_e32 v141, 0xbfb8aa3b, v141
	v_exp_f32_e32 v135, v135
	v_exp_f32_e32 v137, v137
	v_exp_f32_e32 v140, v140
	v_exp_f32_e32 v139, v139
	v_exp_f32_e32 v141, v141
	v_add_f32_e32 v134, 1.0, v134
	v_add_f32_e32 v138, 1.0, v138
	v_rcp_f32_e32 v134, v134
	v_add_f32_e32 v136, 1.0, v136
	v_add_f32_e32 v135, 1.0, v135
	v_add_f32_e32 v137, 1.0, v137
	v_rcp_f32_e32 v138, v138
	v_add_f32_e32 v140, 1.0, v140
	v_rcp_f32_e32 v136, v136
	v_add_f32_e32 v139, 1.0, v139
	v_add_f32_e32 v141, 1.0, v141
	v_rcp_f32_e32 v135, v135
	v_rcp_f32_e32 v137, v137
	v_rcp_f32_e32 v140, v140
	v_rcp_f32_e32 v139, v139
	v_rcp_f32_e32 v141, v141
	v_mul_f32_e32 v134, v75, v134
	v_mul_f32_e32 v138, v74, v138
	v_mul_f32_e32 v136, v71, v136
	v_mul_f32_e32 v135, v77, v135
	v_mul_f32_e32 v137, v73, v137
	v_cvt_pk_bf16_f32 v134, v138, v134
	v_mul_f32_e32 v140, v70, v140
	v_mul_f32_e32 v139, v76, v139
	v_mul_f32_e32 v141, v72, v141
	v_cvt_pk_bf16_f32 v135, v139, v135
	v_cvt_pk_bf16_f32 v136, v140, v136
	v_cvt_pk_bf16_f32 v137, v141, v137
	global_store_dwordx4 v[142:143], v[134:137], off offset:2304
	s_nop 1
	v_add_u32_e32 v134, 0x80, v0
	v_mad_i64_i32 v[134:135], s[0:1], v134, s29, v[146:147]
	v_lshl_add_u64 v[144:145], v[134:135], 0, v[148:149]
	v_add_co_u32_e32 v134, vcc, s98, v144
	s_nop 1
	v_addc_co_u32_e32 v135, vcc, 0, v145, vcc
	s_waitcnt vmcnt(12)
; __device__ __forceinline__ float sigmoidf_(float g) { return __builtin_amdgcn_rcpf(1.f + __expf(-g)); }
; __device__ __forceinline__ u32x4 pack8(const f32x4& a, const f32x4& b) { u32x4 w; w.x = cvt_pk_bf16(a[0], a[1]); w.y = cvt_pk_bf16(a[2], a[3]); w.z = cvt_pk_bf16(b[0], b[1]); w.w = cvt_pk_bf16(b[2], b[3]); return w; }
; __device__ __forceinline__ void unpack8(const u32x4& w, float (&v)[8]) { v[0] = bf_lo(w.x); v[1] = bf_hi(w.x); v[2] = bf_lo(w.y); v[3] = bf_hi(w.y); v[4] = bf_lo(w.z); v[5] = bf_hi(w.z); v[6] = bf_lo(w.w); v[7] = bf_hi(w.w); }
;     __device__ __forceinline__ void apply(const Ld& d, int row, int c0, int, int, int, const f32x4& a0, const f32x4& b0, const f32x4& a1, const f32x4& b1) const { half(d.g0, d.p0, row, c0, a0, b0); half(d.g1, d.p1, row, c0 + 128, a1, b1); }
;     __device__ __forceinline__ void half(const u32x4& gw, int row, int col, const f32x4& a, const f32x4& b) const {
;         float g[8]; unpack8(gw, g);
;         f32x4 r0, r1;
; #pragma unroll
;         for (int i = 0; i < 4; ++i) { r0[i] = a[i] * sigmoidf_(g[i]); r1[i] = b[i] * sigmoidf_(g[4 + i]); }
;         *(u32x4*)(proj + (size_t)row * PW + C_MPOOL + col) = pack8(r0, r1);
;     }
;     __device__ __forceinline__ void apply(const Ld& d, int row, int c0, int, int, int, const f32x4& a0, const f32x4& b0, const f32x4& a1, const f32x4& b1) const { half(d.g0, row, c0, a0, b0); half(d.g1, row, c0 + 128, a1, b1); }
	v_mov_b32_e32 v150, v178
	v_mov_b32_e32 v151, v179
	v_mov_b32_e32 v152, v180
	v_mov_b32_e32 v153, v181
	v_mov_b32_e32 v154, v204
	v_mov_b32_e32 v155, v205
	v_mov_b32_e32 v156, v206
	v_mov_b32_e32 v157, v207
	v_add_u32_e32 v134, 0x90, v0
	v_mad_i64_i32 v[134:135], s[0:1], v134, s29, v[146:147]
	v_lshl_add_u64 v[142:143], v[134:135], 0, v[148:149]
	v_add_co_u32_e32 v134, vcc, s98, v142
	s_nop 0
	v_lshlrev_b32_e32 v158, 16, v150
	v_addc_co_u32_e32 v135, vcc, 0, v143, vcc
	v_mov_b32_e32 v138, v208
	v_mov_b32_e32 v139, v209
	v_mov_b32_e32 v140, v210
	v_mov_b32_e32 v141, v211
	s_nop 0
	v_mov_b32_e32 v134, v212
	v_mov_b32_e32 v135, v213
	v_mov_b32_e32 v136, v214
	v_mov_b32_e32 v137, v215
	v_and_b32_e32 v150, 0xffff0000, v150
	v_lshlrev_b32_e32 v159, 16, v151
	v_and_b32_e32 v151, 0xffff0000, v151
	v_lshlrev_b32_e32 v160, 16, v152
	v_and_b32_e32 v152, 0xffff0000, v152
	v_lshlrev_b32_e32 v161, 16, v153
	v_and_b32_e32 v153, 0xffff0000, v153
	v_mul_f32_e32 v150, 0xbfb8aa3b, v150
	v_mul_f32_e32 v152, 0xbfb8aa3b, v152
	v_mul_f32_e32 v151, 0xbfb8aa3b, v151
	v_mul_f32_e32 v153, 0xbfb8aa3b, v153
	v_mul_f32_e32 v158, 0xbfb8aa3b, v158
	v_mul_f32_e32 v160, 0xbfb8aa3b, v160
	v_exp_f32_e32 v150, v150
	v_exp_f32_e32 v152, v152
	v_mul_f32_e32 v159, 0xbfb8aa3b, v159
	v_mul_f32_e32 v161, 0xbfb8aa3b, v161
	v_exp_f32_e32 v151, v151
	v_exp_f32_e32 v153, v153
	v_exp_f32_e32 v158, v158
	v_exp_f32_e32 v160, v160
	v_exp_f32_e32 v159, v159
	v_exp_f32_e32 v161, v161
	v_add_f32_e32 v150, 1.0, v150
	v_add_f32_e32 v152, 1.0, v152
	v_add_f32_e32 v151, 1.0, v151
	v_add_f32_e32 v153, 1.0, v153
	v_add_f32_e32 v158, 1.0, v158
	v_add_f32_e32 v160, 1.0, v160
	v_rcp_f32_e32 v150, v150
	v_rcp_f32_e32 v152, v152
	v_add_f32_e32 v159, 1.0, v159
	v_add_f32_e32 v161, 1.0, v161
	v_rcp_f32_e32 v151, v151
	v_rcp_f32_e32 v153, v153
	v_rcp_f32_e32 v158, v158
	v_rcp_f32_e32 v160, v160
	v_rcp_f32_e32 v159, v159
	v_rcp_f32_e32 v161, v161
	v_mul_f32_e32 v150, v67, v150
	v_mul_f32_e32 v152, v63, v152
	v_mul_f32_e32 v151, v69, v151
	v_mul_f32_e32 v153, v65, v153
	v_mul_f32_e32 v158, v66, v158
	v_mul_f32_e32 v160, v62, v160
	v_mul_f32_e32 v159, v68, v159
	v_mul_f32_e32 v161, v64, v161
	v_cvt_pk_bf16_f32 v150, v158, v150
	v_cvt_pk_bf16_f32 v151, v159, v151
	v_cvt_pk_bf16_f32 v152, v160, v152
	v_cvt_pk_bf16_f32 v153, v161, v153
	global_store_dwordx4 v[144:145], v[150:153], off offset:2048
	s_nop 1
	v_lshlrev_b32_e32 v150, 16, v154
	v_and_b32_e32 v151, 0xffff0000, v154
	v_lshlrev_b32_e32 v152, 16, v155
	v_and_b32_e32 v153, 0xffff0000, v155
	v_lshlrev_b32_e32 v154, 16, v156
	v_and_b32_e32 v155, 0xffff0000, v156
	v_lshlrev_b32_e32 v156, 16, v157
	v_and_b32_e32 v157, 0xffff0000, v157
	v_mul_f32_e32 v150, 0xbfb8aa3b, v150
	v_mul_f32_e32 v151, 0xbfb8aa3b, v151
	v_mul_f32_e32 v152, 0xbfb8aa3b, v152
	v_mul_f32_e32 v153, 0xbfb8aa3b, v153
	v_exp_f32_e32 v150, v150
	v_mul_f32_e32 v154, 0xbfb8aa3b, v154
	v_exp_f32_e32 v151, v151
	v_mul_f32_e32 v155, 0xbfb8aa3b, v155
	v_exp_f32_e32 v152, v152
	v_mul_f32_e32 v156, 0xbfb8aa3b, v156
	v_exp_f32_e32 v153, v153
	v_mul_f32_e32 v157, 0xbfb8aa3b, v157
	v_exp_f32_e32 v154, v154
	v_exp_f32_e32 v155, v155
	v_exp_f32_e32 v156, v156
	v_exp_f32_e32 v157, v157
	v_add_f32_e32 v150, 1.0, v150
	v_add_f32_e32 v151, 1.0, v151
	v_add_f32_e32 v152, 1.0, v152
	v_add_f32_e32 v153, 1.0, v153
	v_rcp_f32_e32 v150, v150
	v_add_f32_e32 v154, 1.0, v154
	v_rcp_f32_e32 v151, v151
	v_add_f32_e32 v155, 1.0, v155
	v_rcp_f32_e32 v152, v152
	v_add_f32_e32 v156, 1.0, v156
	v_rcp_f32_e32 v153, v153
	v_add_f32_e32 v157, 1.0, v157
	v_rcp_f32_e32 v154, v154
	v_rcp_f32_e32 v155, v155
	v_rcp_f32_e32 v156, v156
	v_rcp_f32_e32 v157, v157
	v_mul_f32_e32 v150, v58, v150
	v_mul_f32_e32 v151, v59, v151
	v_mul_f32_e32 v152, v60, v152
	v_mul_f32_e32 v153, v61, v153
	v_mul_f32_e32 v154, v54, v154
	v_mul_f32_e32 v155, v55, v155
	v_mul_f32_e32 v156, v56, v156
	v_mul_f32_e32 v157, v57, v157
	v_cvt_pk_bf16_f32 v150, v150, v151
	v_cvt_pk_bf16_f32 v151, v152, v153
	v_cvt_pk_bf16_f32 v152, v154, v155
	v_cvt_pk_bf16_f32 v153, v156, v157
	global_store_dwordx4 v[144:145], v[150:153], off offset:2304
	s_nop 0
	v_lshlrev_b32_e32 v144, 16, v138
	v_and_b32_e32 v138, 0xffff0000, v138
	v_lshlrev_b32_e32 v145, 16, v139
	v_and_b32_e32 v139, 0xffff0000, v139
	v_lshlrev_b32_e32 v150, 16, v140
	v_and_b32_e32 v140, 0xffff0000, v140
	v_lshlrev_b32_e32 v151, 16, v141
	v_and_b32_e32 v141, 0xffff0000, v141
	v_mul_f32_e32 v138, 0xbfb8aa3b, v138
	v_mul_f32_e32 v144, 0xbfb8aa3b, v144
	v_exp_f32_e32 v138, v138
	v_mul_f32_e32 v140, 0xbfb8aa3b, v140
	v_mul_f32_e32 v139, 0xbfb8aa3b, v139
	v_mul_f32_e32 v141, 0xbfb8aa3b, v141
	v_exp_f32_e32 v144, v144
	v_mul_f32_e32 v150, 0xbfb8aa3b, v150
	v_exp_f32_e32 v140, v140
	v_mul_f32_e32 v145, 0xbfb8aa3b, v145
	v_mul_f32_e32 v151, 0xbfb8aa3b, v151
	v_exp_f32_e32 v139, v139
	v_exp_f32_e32 v141, v141
	v_exp_f32_e32 v150, v150
	v_exp_f32_e32 v145, v145
	v_exp_f32_e32 v151, v151
	v_add_f32_e32 v138, 1.0, v138
	v_add_f32_e32 v144, 1.0, v144
	v_rcp_f32_e32 v138, v138
	v_add_f32_e32 v140, 1.0, v140
	v_add_f32_e32 v139, 1.0, v139
	v_add_f32_e32 v141, 1.0, v141
	v_rcp_f32_e32 v144, v144
	v_add_f32_e32 v150, 1.0, v150
	v_rcp_f32_e32 v140, v140
	v_add_f32_e32 v145, 1.0, v145
	v_add_f32_e32 v151, 1.0, v151
	v_rcp_f32_e32 v139, v139
	v_rcp_f32_e32 v141, v141
	v_rcp_f32_e32 v150, v150
	v_rcp_f32_e32 v145, v145
	v_rcp_f32_e32 v151, v151
	v_mul_f32_e32 v138, v51, v138
	v_mul_f32_e32 v144, v50, v144
	v_mul_f32_e32 v140, v47, v140
	v_mul_f32_e32 v139, v53, v139
	v_mul_f32_e32 v141, v49, v141
	v_cvt_pk_bf16_f32 v138, v144, v138
	v_mul_f32_e32 v150, v46, v150
	v_mul_f32_e32 v145, v52, v145
	v_mul_f32_e32 v151, v48, v151
; __device__ __forceinline__ float sigmoidf_(float g) { return __builtin_amdgcn_rcpf(1.f + __expf(-g)); }
; __device__ __forceinline__ u32x4 pack8(const f32x4& a, const f32x4& b) { u32x4 w; w.x = cvt_pk_bf16(a[0], a[1]); w.y = cvt_pk_bf16(a[2], a[3]); w.z = cvt_pk_bf16(b[0], b[1]); w.w = cvt_pk_bf16(b[2], b[3]); return w; }
; __device__ __forceinline__ void unpack8(const u32x4& w, float (&v)[8]) { v[0] = bf_lo(w.x); v[1] = bf_hi(w.x); v[2] = bf_lo(w.y); v[3] = bf_hi(w.y); v[4] = bf_lo(w.z); v[5] = bf_hi(w.z); v[6] = bf_lo(w.w); v[7] = bf_hi(w.w); }
;     __device__ __forceinline__ void apply(const Ld& d, int row, int c0, int, int, int, const f32x4& a0, const f32x4& b0, const f32x4& a1, const f32x4& b1) const { half(d.g0, d.p0, row, c0, a0, b0); half(d.g1, d.p1, row, c0 + 128, a1, b1); }
;     __device__ __forceinline__ void half(const u32x4& gw, int row, int col, const f32x4& a, const f32x4& b) const {
;         float g[8]; unpack8(gw, g);
;         f32x4 r0, r1;
; #pragma unroll
;         for (int i = 0; i < 4; ++i) { r0[i] = a[i] * sigmoidf_(g[i]); r1[i] = b[i] * sigmoidf_(g[4 + i]); }
;         *(u32x4*)(proj + (size_t)row * PW + C_MPOOL + col) = pack8(r0, r1);
;     }
;     __device__ __forceinline__ void apply(const Ld& d, int row, int c0, int, int, int, const f32x4& a0, const f32x4& b0, const f32x4& a1, const f32x4& b1) const { half(d.g0, row, c0, a0, b0); half(d.g1, row, c0 + 128, a1, b1); }
	v_cvt_pk_bf16_f32 v139, v145, v139
	v_cvt_pk_bf16_f32 v140, v150, v140
	v_cvt_pk_bf16_f32 v141, v151, v141
	global_store_dwordx4 v[142:143], v[138:141], off offset:2048
	s_nop 1
	v_lshlrev_b32_e32 v138, 16, v134
	v_and_b32_e32 v134, 0xffff0000, v134
	v_lshlrev_b32_e32 v139, 16, v135
	v_and_b32_e32 v135, 0xffff0000, v135
	v_lshlrev_b32_e32 v140, 16, v136
	v_and_b32_e32 v136, 0xffff0000, v136
	v_lshlrev_b32_e32 v141, 16, v137
	v_and_b32_e32 v137, 0xffff0000, v137
	v_mul_f32_e32 v134, 0xbfb8aa3b, v134
	v_mul_f32_e32 v138, 0xbfb8aa3b, v138
	v_exp_f32_e32 v134, v134
	v_mul_f32_e32 v136, 0xbfb8aa3b, v136
	v_mul_f32_e32 v135, 0xbfb8aa3b, v135
	v_mul_f32_e32 v137, 0xbfb8aa3b, v137
	v_exp_f32_e32 v138, v138
	v_mul_f32_e32 v140, 0xbfb8aa3b, v140
	v_exp_f32_e32 v136, v136
	v_mul_f32_e32 v139, 0xbfb8aa3b, v139
	v_mul_f32_e32 v141, 0xbfb8aa3b, v141
	v_exp_f32_e32 v135, v135
	v_exp_f32_e32 v137, v137
	v_exp_f32_e32 v140, v140
	v_exp_f32_e32 v139, v139
	v_exp_f32_e32 v141, v141
	v_add_f32_e32 v134, 1.0, v134
	v_add_f32_e32 v138, 1.0, v138
	v_rcp_f32_e32 v134, v134
	v_add_f32_e32 v136, 1.0, v136
	v_add_f32_e32 v135, 1.0, v135
	v_add_f32_e32 v137, 1.0, v137
	v_rcp_f32_e32 v138, v138
	v_add_f32_e32 v140, 1.0, v140
	v_rcp_f32_e32 v136, v136
	v_add_f32_e32 v139, 1.0, v139
	v_add_f32_e32 v141, 1.0, v141
	v_rcp_f32_e32 v135, v135
	v_rcp_f32_e32 v137, v137
	v_rcp_f32_e32 v140, v140
	v_rcp_f32_e32 v139, v139
	v_rcp_f32_e32 v141, v141
	v_mul_f32_e32 v134, v43, v134
	v_mul_f32_e32 v138, v42, v138
	v_mul_f32_e32 v136, v39, v136
	v_mul_f32_e32 v135, v45, v135
	v_mul_f32_e32 v137, v41, v137
	v_cvt_pk_bf16_f32 v134, v138, v134
	v_mul_f32_e32 v140, v38, v140
	v_mul_f32_e32 v139, v44, v139
	v_mul_f32_e32 v141, v40, v141
	v_cvt_pk_bf16_f32 v135, v139, v135
	v_cvt_pk_bf16_f32 v136, v140, v136
	v_cvt_pk_bf16_f32 v137, v141, v137
	global_store_dwordx4 v[142:143], v[134:137], off offset:2304
	s_nop 1
	v_add_u32_e32 v134, 0xa0, v0
	v_mad_i64_i32 v[134:135], s[0:1], v134, s29, v[146:147]
	v_lshl_add_u64 v[144:145], v[134:135], 0, v[148:149]
	v_add_co_u32_e32 v134, vcc, s98, v144
	v_add_u32_e32 v0, 0xb0, v0
	s_nop 0
	v_addc_co_u32_e32 v135, vcc, 0, v145, vcc
	s_waitcnt vmcnt(12)
	v_mov_b32_e32 v150, v216
	v_mov_b32_e32 v151, v217
	v_mov_b32_e32 v152, v218
	v_mov_b32_e32 v153, v219
	v_mov_b32_e32 v154, v220
	v_mov_b32_e32 v155, v221
	v_mov_b32_e32 v156, v222
	v_mov_b32_e32 v157, v223
	v_mad_i64_i32 v[134:135], s[0:1], v0, s29, v[146:147]
	v_lshl_add_u64 v[142:143], v[134:135], 0, v[148:149]
	v_add_co_u32_e32 v134, vcc, s98, v142
	s_nop 0
	v_and_b32_e32 v146, 0xffff0000, v150
	v_addc_co_u32_e32 v135, vcc, 0, v143, vcc
	v_mov_b32_e32 v138, v224
	v_mov_b32_e32 v139, v225
	v_mov_b32_e32 v140, v226
	v_mov_b32_e32 v141, v227
	s_nop 0
	v_mov_b32_e32 v134, v244
	v_mov_b32_e32 v135, v245
	v_mov_b32_e32 v136, v246
	v_mov_b32_e32 v137, v247
	v_lshlrev_b32_e32 v147, 16, v151
	v_and_b32_e32 v148, 0xffff0000, v151
	v_lshlrev_b32_e32 v149, 16, v152
	v_lshlrev_b32_e32 v0, 16, v150
	v_and_b32_e32 v150, 0xffff0000, v152
	v_lshlrev_b32_e32 v151, 16, v153
	v_and_b32_e32 v152, 0xffff0000, v153
	v_mul_f32_e32 v149, 0xbfb8aa3b, v149
	v_mul_f32_e32 v146, 0xbfb8aa3b, v146
	v_mul_f32_e32 v147, 0xbfb8aa3b, v147
	v_mul_f32_e32 v148, 0xbfb8aa3b, v148
	v_mul_f32_e32 v0, 0xbfb8aa3b, v0
	v_exp_f32_e32 v149, v149
	v_exp_f32_e32 v146, v146
	v_mul_f32_e32 v150, 0xbfb8aa3b, v150
	v_exp_f32_e32 v147, v147
	v_mul_f32_e32 v151, 0xbfb8aa3b, v151
	v_exp_f32_e32 v148, v148
	v_mul_f32_e32 v152, 0xbfb8aa3b, v152
	v_exp_f32_e32 v0, v0
	v_exp_f32_e32 v150, v150
	v_exp_f32_e32 v151, v151
	v_exp_f32_e32 v152, v152
	v_add_f32_e32 v149, 1.0, v149
	v_add_f32_e32 v146, 1.0, v146
	v_add_f32_e32 v147, 1.0, v147
	v_add_f32_e32 v148, 1.0, v148
	v_add_f32_e32 v0, 1.0, v0
	v_rcp_f32_e32 v149, v149
	v_rcp_f32_e32 v146, v146
	v_add_f32_e32 v150, 1.0, v150
	v_rcp_f32_e32 v147, v147
	v_add_f32_e32 v151, 1.0, v151
	v_rcp_f32_e32 v148, v148
	v_add_f32_e32 v152, 1.0, v152
	v_rcp_f32_e32 v0, v0
	v_rcp_f32_e32 v150, v150
	v_rcp_f32_e32 v151, v151
	v_rcp_f32_e32 v152, v152
	v_mul_f32_e32 v149, v30, v149
	v_mul_f32_e32 v146, v35, v146
	v_mul_f32_e32 v147, v36, v147
	v_mul_f32_e32 v148, v37, v148
	v_mul_f32_e32 v0, v34, v0
	v_mul_f32_e32 v150, v31, v150
	v_mul_f32_e32 v151, v32, v151
	v_mul_f32_e32 v152, v33, v152
	v_cvt_pk_bf16_f32 v146, v0, v146
	v_cvt_pk_bf16_f32 v147, v147, v148
	v_cvt_pk_bf16_f32 v148, v149, v150
	v_cvt_pk_bf16_f32 v149, v151, v152
	global_store_dwordx4 v[144:145], v[146:149], off offset:2048
	v_lshlrev_b32_e32 v0, 16, v154
	v_and_b32_e32 v150, 0xffff0000, v156
	v_and_b32_e32 v146, 0xffff0000, v154
	v_lshlrev_b32_e32 v147, 16, v155
	v_and_b32_e32 v148, 0xffff0000, v155
	v_lshlrev_b32_e32 v149, 16, v156
	v_lshlrev_b32_e32 v151, 16, v157
	v_and_b32_e32 v152, 0xffff0000, v157
; __device__ __forceinline__ float sigmoidf_(float g) { return __builtin_amdgcn_rcpf(1.f + __expf(-g)); }
; __device__ __forceinline__ u32x4 pack8(const f32x4& a, const f32x4& b) { u32x4 w; w.x = cvt_pk_bf16(a[0], a[1]); w.y = cvt_pk_bf16(a[2], a[3]); w.z = cvt_pk_bf16(b[0], b[1]); w.w = cvt_pk_bf16(b[2], b[3]); return w; }
; __device__ __forceinline__ void unpack8(const u32x4& w, float (&v)[8]) { v[0] = bf_lo(w.x); v[1] = bf_hi(w.x); v[2] = bf_lo(w.y); v[3] = bf_hi(w.y); v[4] = bf_lo(w.z); v[5] = bf_hi(w.z); v[6] = bf_lo(w.w); v[7] = bf_hi(w.w); }
;     __device__ __forceinline__ void apply(const Ld& d, int row, int c0, int, int, int, const f32x4& a0, const f32x4& b0, const f32x4& a1, const f32x4& b1) const { half(d.g0, d.p0, row, c0, a0, b0); half(d.g1, d.p1, row, c0 + 128, a1, b1); }
;     __device__ __forceinline__ void half(const u32x4& gw, int row, int col, const f32x4& a, const f32x4& b) const {
;         float g[8]; unpack8(gw, g);
;         f32x4 r0, r1;
; #pragma unroll
;         for (int i = 0; i < 4; ++i) { r0[i] = a[i] * sigmoidf_(g[i]); r1[i] = b[i] * sigmoidf_(g[4 + i]); }
;         *(u32x4*)(proj + (size_t)row * PW + C_MPOOL + col) = pack8(r0, r1);
;     }
;     __device__ __forceinline__ void apply(const Ld& d, int row, int c0, int, int, int, const f32x4& a0, const f32x4& b0, const f32x4& a1, const f32x4& b1) const { half(d.g0, row, c0, a0, b0); half(d.g1, row, c0 + 128, a1, b1); }
	v_mul_f32_e32 v0, 0xbfb8aa3b, v0
	v_mul_f32_e32 v149, 0xbfb8aa3b, v149
	v_mul_f32_e32 v146, 0xbfb8aa3b, v146
	v_mul_f32_e32 v147, 0xbfb8aa3b, v147
	v_mul_f32_e32 v148, 0xbfb8aa3b, v148
	v_exp_f32_e32 v0, v0
	v_exp_f32_e32 v149, v149
	v_exp_f32_e32 v146, v146
	v_mul_f32_e32 v150, 0xbfb8aa3b, v150
	v_exp_f32_e32 v147, v147
	v_mul_f32_e32 v151, 0xbfb8aa3b, v151
	v_exp_f32_e32 v148, v148
	v_mul_f32_e32 v152, 0xbfb8aa3b, v152
	v_exp_f32_e32 v150, v150
	v_exp_f32_e32 v151, v151
	v_exp_f32_e32 v152, v152
	v_add_f32_e32 v0, 1.0, v0
	v_add_f32_e32 v149, 1.0, v149
	v_add_f32_e32 v146, 1.0, v146
	v_add_f32_e32 v147, 1.0, v147
	v_add_f32_e32 v148, 1.0, v148
	v_rcp_f32_e32 v0, v0
	v_rcp_f32_e32 v149, v149
	v_rcp_f32_e32 v146, v146
	v_add_f32_e32 v150, 1.0, v150
	v_rcp_f32_e32 v147, v147
	v_add_f32_e32 v151, 1.0, v151
	v_rcp_f32_e32 v148, v148
	v_add_f32_e32 v152, 1.0, v152
	v_rcp_f32_e32 v150, v150
	v_rcp_f32_e32 v151, v151
	v_rcp_f32_e32 v152, v152
	v_mul_f32_e32 v0, v26, v0
	v_mul_f32_e32 v149, v22, v149
	v_mul_f32_e32 v146, v27, v146
	v_mul_f32_e32 v147, v28, v147
	v_mul_f32_e32 v148, v29, v148
	v_mul_f32_e32 v150, v23, v150
	v_mul_f32_e32 v151, v24, v151
	v_mul_f32_e32 v152, v25, v152
	v_cvt_pk_bf16_f32 v146, v0, v146
	v_cvt_pk_bf16_f32 v147, v147, v148
	v_cvt_pk_bf16_f32 v148, v149, v150
	v_cvt_pk_bf16_f32 v149, v151, v152
	global_store_dwordx4 v[144:145], v[146:149], off offset:2304
	s_nop 0
	v_lshlrev_b32_e32 v0, 16, v138
	v_and_b32_e32 v138, 0xffff0000, v138
	v_lshlrev_b32_e32 v144, 16, v139
	v_and_b32_e32 v139, 0xffff0000, v139
	v_lshlrev_b32_e32 v145, 16, v140
	v_and_b32_e32 v140, 0xffff0000, v140
	v_lshlrev_b32_e32 v146, 16, v141
	v_and_b32_e32 v141, 0xffff0000, v141
	v_mul_f32_e32 v138, 0xbfb8aa3b, v138
	v_mul_f32_e32 v140, 0xbfb8aa3b, v140
	v_mul_f32_e32 v139, 0xbfb8aa3b, v139
	v_mul_f32_e32 v0, 0xbfb8aa3b, v0
	v_mul_f32_e32 v145, 0xbfb8aa3b, v145
	v_exp_f32_e32 v138, v138
	v_exp_f32_e32 v140, v140
	v_mul_f32_e32 v144, 0xbfb8aa3b, v144
	v_exp_f32_e32 v139, v139
	v_mul_f32_e32 v141, 0xbfb8aa3b, v141
	v_exp_f32_e32 v0, v0
	v_exp_f32_e32 v145, v145
	v_exp_f32_e32 v144, v144
	v_mul_f32_e32 v146, 0xbfb8aa3b, v146
	v_exp_f32_e32 v141, v141
	v_exp_f32_e32 v146, v146
	v_add_f32_e32 v138, 1.0, v138
	v_add_f32_e32 v140, 1.0, v140
	v_add_f32_e32 v139, 1.0, v139
	v_add_f32_e32 v0, 1.0, v0
	v_add_f32_e32 v145, 1.0, v145
	v_rcp_f32_e32 v138, v138
	v_rcp_f32_e32 v140, v140
	v_add_f32_e32 v144, 1.0, v144
	v_rcp_f32_e32 v139, v139
	v_add_f32_e32 v141, 1.0, v141
	v_rcp_f32_e32 v0, v0
	v_rcp_f32_e32 v145, v145
	v_rcp_f32_e32 v144, v144
	v_add_f32_e32 v146, 1.0, v146
	v_rcp_f32_e32 v141, v141
	v_rcp_f32_e32 v146, v146
	v_mul_f32_e32 v138, v19, v138
	v_mul_f32_e32 v140, v11, v140
	v_mul_f32_e32 v139, v21, v139
	v_mul_f32_e32 v0, v18, v0
	v_mul_f32_e32 v145, v10, v145
	v_mul_f32_e32 v144, v20, v144
	v_mul_f32_e32 v141, v13, v141
	v_cvt_pk_bf16_f32 v138, v0, v138
	v_cvt_pk_bf16_f32 v139, v144, v139
	v_cvt_pk_bf16_f32 v140, v145, v140
	v_mul_f32_e32 v146, v12, v146
	v_cvt_pk_bf16_f32 v141, v146, v141
	global_store_dwordx4 v[142:143], v[138:141], off offset:2048
	v_lshlrev_b32_e32 v0, 16, v134
	v_and_b32_e32 v134, 0xffff0000, v134
	v_lshlrev_b32_e32 v138, 16, v135
	v_and_b32_e32 v135, 0xffff0000, v135
	v_lshlrev_b32_e32 v139, 16, v136
	v_and_b32_e32 v136, 0xffff0000, v136
	v_lshlrev_b32_e32 v140, 16, v137
	v_and_b32_e32 v137, 0xffff0000, v137
	v_mul_f32_e32 v134, 0xbfb8aa3b, v134
	v_mul_f32_e32 v136, 0xbfb8aa3b, v136
	v_mul_f32_e32 v135, 0xbfb8aa3b, v135
	v_mul_f32_e32 v137, 0xbfb8aa3b, v137
	v_mul_f32_e32 v0, 0xbfb8aa3b, v0
	v_mul_f32_e32 v139, 0xbfb8aa3b, v139
	v_exp_f32_e32 v134, v134
	v_exp_f32_e32 v136, v136
	v_mul_f32_e32 v138, 0xbfb8aa3b, v138
	v_mul_f32_e32 v140, 0xbfb8aa3b, v140
	v_exp_f32_e32 v135, v135
	v_exp_f32_e32 v137, v137
	v_exp_f32_e32 v0, v0
	v_exp_f32_e32 v139, v139
	v_exp_f32_e32 v138, v138
	v_exp_f32_e32 v140, v140
	v_add_f32_e32 v134, 1.0, v134
	v_add_f32_e32 v136, 1.0, v136
	v_add_f32_e32 v135, 1.0, v135
	v_add_f32_e32 v137, 1.0, v137
	v_add_f32_e32 v0, 1.0, v0
	v_add_f32_e32 v139, 1.0, v139
	v_rcp_f32_e32 v134, v134
	v_rcp_f32_e32 v136, v136
	v_add_f32_e32 v138, 1.0, v138
	v_add_f32_e32 v140, 1.0, v140
	v_rcp_f32_e32 v135, v135
	v_rcp_f32_e32 v137, v137
	v_rcp_f32_e32 v0, v0
	v_rcp_f32_e32 v139, v139
	v_rcp_f32_e32 v138, v138
	v_rcp_f32_e32 v140, v140
	v_mul_f32_e32 v134, v7, v134
	v_mul_f32_e32 v136, v3, v136
	v_mul_f32_e32 v135, v9, v135
	v_mul_f32_e32 v137, v5, v137
	v_mul_f32_e32 v0, v6, v0
	v_mul_f32_e32 v139, v2, v139
	v_mul_f32_e32 v138, v8, v138
	v_mul_f32_e32 v140, v4, v140
	v_cvt_pk_bf16_f32 v134, v0, v134
	v_cvt_pk_bf16_f32 v135, v138, v135
	v_cvt_pk_bf16_f32 v136, v139, v136
	v_cvt_pk_bf16_f32 v137, v140, v137
	global_store_dwordx4 v[142:143], v[134:137], off offset:2304
